# seam 0 (phase 1): next 4 rows prefetched with scalar-base loads into staging regs, counted vmcnt(16) at body top; on top of v53
# speedup vs baseline: 1.0048x; 1.0012x over previous
.LBB0_71:
	s_or_b64 exec, exec, s[0:1]
	s_lshl_b32 s0, s68, 3
	s_abs_i32 s1, s0
	v_cvt_f32_u32_e32 v0, s1
	s_sub_i32 s4, 0, s1
	s_add_i32 s3, s0, 0x9fff
	s_xor_b32 s0, s3, s0
	v_rcp_iflag_f32_e32 v0, v0
	s_abs_i32 s3, s3
	s_ashr_i32 s0, s0, 31
	v_lshrrev_b32_e32 v195, 6, v146
	v_mul_f32_e32 v0, 0x4f7ffffe, v0
	v_cvt_u32_f32_e32 v0, v0
	v_lshl_add_u32 v150, s2, 3, v195
	v_and_b32_e32 v151, 0xfc, v164
	v_mov_b32_e32 v145, 0
	v_readfirstlane_b32 s5, v0
	s_mul_i32 s4, s4, s5
	s_mul_hi_u32 s4, s5, s4
	s_add_i32 s5, s5, s4
	s_mul_hi_u32 s4, s3, s5
	s_mul_i32 s5, s4, s1
	s_sub_i32 s3, s3, s5
	s_add_i32 s6, s4, 1
	s_sub_i32 s5, s3, s1
	s_cmp_ge_u32 s3, s1
	s_cselect_b32 s4, s6, s4
	s_cselect_b32 s3, s5, s3
	s_add_i32 s5, s4, 1
	s_cmp_ge_u32 s3, s1
	s_cselect_b32 s1, s5, s4
	s_xor_b32 s1, s1, s0
	s_sub_i32 s3, s1, s0
	s_add_i32 s0, s3, 3
	s_ashr_i32 s1, s0, 31
	s_lshr_b32 s1, s1, 30
	s_add_i32 s0, s0, s1
	s_and_b32 s0, s0, -4
	v_mul_lo_u32 v16, s0, v150
	v_add_u32_e32 v0, s0, v16
	v_min_i32_e32 v116, 0xa000, v0
	v_or_b32_e32 v160, 0x100, v151
	v_or_b32_e32 v161, 0x200, v151
	v_or_b32_e32 v162, 0x300, v151
	v_cmp_lt_i32_e32 vcc, v16, v116
	v_lshlrev_b32_e32 v144, 2, v151
	v_mbcnt_lo_u32_b32 v167, -1, 0
	v_and_b32_e32 v147, 63, v146
	s_and_saveexec_b64 s[6:7], vcc
	s_cbranch_execz .LBB0_76
	global_load_dwordx4 v[0:3], v144, s[66:67] offset:3072
	global_load_dwordx4 v[4:7], v144, s[66:67] offset:2048
	global_load_dwordx4 v[8:11], v144, s[66:67] offset:1024
	global_load_dwordx4 v[12:15], v144, s[66:67]
	v_mbcnt_hi_u32_b32 v17, -1, v167
	v_and_b32_e32 v18, 64, v17
	v_add_u32_e32 v18, 64, v18
	v_xor_b32_e32 v19, 32, v17
	v_cmp_lt_i32_e32 vcc, v19, v18
	s_mov_b64 s[0:1], 0x3223e00
	v_mov_b32_e32 v123, -1
	v_cndmask_b32_e32 v19, v17, v19, vcc
	v_lshlrev_b32_e32 v117, 2, v19
	v_xor_b32_e32 v19, 16, v17
	v_cmp_lt_i32_e32 vcc, v19, v18
	s_mov_b64 s[8:9], 0
	s_movk_i32 s17, 0x2000
	v_cndmask_b32_e32 v19, v17, v19, vcc
	v_lshlrev_b32_e32 v118, 2, v19
	v_xor_b32_e32 v19, 8, v17
	v_cmp_lt_i32_e32 vcc, v19, v18
	s_mov_b64 s[14:15], 0x1000
	s_mov_b32 s16, 0x3a800000
	v_cndmask_b32_e32 v19, v17, v19, vcc
	v_lshlrev_b32_e32 v119, 2, v19
	v_xor_b32_e32 v19, 4, v17
	v_cmp_lt_i32_e32 vcc, v19, v18
	s_mov_b32 s18, 0x358637bd
	s_mov_b32 s19, 0x800000
	v_cndmask_b32_e32 v19, v17, v19, vcc
	v_lshlrev_b32_e32 v120, 2, v19
	v_xor_b32_e32 v19, 2, v17
	v_cmp_lt_i32_e32 vcc, v19, v18
	s_movk_i32 s22, 0xf000
	s_mov_b64 s[20:21], 0x2000
	v_cndmask_b32_e32 v19, v17, v19, vcc
	v_lshlrev_b32_e32 v121, 2, v19
	v_xor_b32_e32 v19, 1, v17
	v_cmp_lt_i32_e32 vcc, v19, v18
	v_mov_b32_e32 v18, v145
	s_nop 0
	v_cndmask_b32_e32 v17, v17, v19, vcc
	v_lshlrev_b32_e32 v122, 2, v17
	v_ashrrev_i32_e32 v17, 31, v16
	v_lshl_add_u64 v[112:113], v[16:17], 0, 1
	v_lshlrev_b64 v[16:17], 11, v[16:17]
	v_lshl_or_b32 v16, v147, 3, v16
	v_lshl_add_u64 v[16:17], s[34:35], 0, v[16:17]
	v_mov_b32_e32 v19, v145
	v_lshl_add_u64 v[114:115], v[16:17], 0, s[0:1]
	v_mov_b32_e32 v16, v145
	v_mov_b32_e32 v17, v145
	v_mov_b64_e32 v[30:31], v[18:19]
	v_mov_b64_e32 v[38:39], v[18:19]
	v_mov_b64_e32 v[46:47], v[18:19]
	v_mov_b64_e32 v[22:23], v[18:19]
	v_mov_b64_e32 v[26:27], v[18:19]
	v_mov_b64_e32 v[34:35], v[18:19]
	v_mov_b64_e32 v[42:43], v[18:19]
	v_mov_b64_e32 v[28:29], v[16:17]
	v_mov_b64_e32 v[36:37], v[16:17]
	v_mov_b64_e32 v[44:45], v[16:17]
	v_mov_b64_e32 v[20:21], v[16:17]
	v_mov_b64_e32 v[24:25], v[16:17]
	v_mov_b64_e32 v[32:33], v[16:17]
	v_mov_b64_e32 v[40:41], v[16:17]
	v_readfirstlane_b32 s32, v112
	v_readfirstlane_b32 s33, v116
	s_nop 3
	s_add_i32 s32, s32, -1
	s_add_i32 s70, s32, 0
	s_cmp_lt_i32 s70, s17
	s_cselect_b32 s88, s52, s54
	s_cselect_b32 s89, s53, s55
	s_cselect_b32 s71, 0, s17
	s_sub_i32 s70, s70, s71
	s_lshl_b32 s70, s70, 12
	s_add_u32 s88, s88, s70
	s_addc_u32 s89, s89, 0
	global_load_dwordx4 v[168:171], v144, s[88:89]
	global_load_dwordx4 v[172:175], v144, s[88:89] offset:1024
	global_load_dwordx4 v[176:179], v144, s[88:89] offset:2048
	global_load_dwordx4 v[180:183], v144, s[88:89] offset:3072
	s_add_i32 s70, s32, 1
	s_cmp_lt_i32 s70, s17
	s_cselect_b32 s88, s52, s54
	s_cselect_b32 s89, s53, s55
	s_cselect_b32 s71, 0, s17
	s_sub_i32 s70, s70, s71
	s_lshl_b32 s70, s70, 12
	s_add_u32 s88, s88, s70
	s_addc_u32 s89, s89, 0
	global_load_dwordx4 v[196:199], v144, s[88:89]
	global_load_dwordx4 v[200:203], v144, s[88:89] offset:1024
	global_load_dwordx4 v[204:207], v144, s[88:89] offset:2048
	global_load_dwordx4 v[208:211], v144, s[88:89] offset:3072
	s_add_i32 s70, s32, 2
	s_cmp_lt_i32 s70, s17
	s_cselect_b32 s88, s52, s54
	s_cselect_b32 s89, s53, s55
	s_cselect_b32 s71, 0, s17
	s_sub_i32 s70, s70, s71
	s_lshl_b32 s70, s70, 12
	s_add_u32 s88, s88, s70
	s_addc_u32 s89, s89, 0
	global_load_dwordx4 v[212:215], v144, s[88:89]
	global_load_dwordx4 v[216:219], v144, s[88:89] offset:1024
	global_load_dwordx4 v[220:223], v144, s[88:89] offset:2048
	global_load_dwordx4 v[224:227], v144, s[88:89] offset:3072
	s_add_i32 s70, s32, 3
	s_cmp_lt_i32 s70, s17
	s_cselect_b32 s88, s52, s54
	s_cselect_b32 s89, s53, s55
	s_cselect_b32 s71, 0, s17
	s_sub_i32 s70, s70, s71
	s_lshl_b32 s70, s70, 12
	s_add_u32 s88, s88, s70
	s_addc_u32 s89, s89, 0
	global_load_dwordx4 v[228:231], v144, s[88:89]
	global_load_dwordx4 v[232:235], v144, s[88:89] offset:1024
	global_load_dwordx4 v[236:239], v144, s[88:89] offset:2048
	global_load_dwordx4 v[240:243], v144, s[88:89] offset:3072
	s_branch .LBB0_74
.LBB0_73:
	s_or_b64 exec, exec, s[0:1]
	s_waitcnt vmcnt(16)
	v_mov_b64_e32 v[100:101], v[168:169]
	v_mov_b64_e32 v[102:103], v[170:171]
	v_mov_b64_e32 v[80:81], v[172:173]
	v_mov_b64_e32 v[82:83], v[174:175]
	v_mov_b64_e32 v[64:65], v[176:177]
	v_mov_b64_e32 v[66:67], v[178:179]
	v_mov_b64_e32 v[48:49], v[180:181]
	v_mov_b64_e32 v[50:51], v[182:183]
	v_mov_b64_e32 v[96:97], v[196:197]
	v_mov_b64_e32 v[98:99], v[198:199]
	v_mov_b64_e32 v[84:85], v[200:201]
	v_mov_b64_e32 v[86:87], v[202:203]
	v_mov_b64_e32 v[68:69], v[204:205]
	v_mov_b64_e32 v[70:71], v[206:207]
	v_mov_b64_e32 v[52:53], v[208:209]
	v_mov_b64_e32 v[54:55], v[210:211]
	v_mov_b64_e32 v[104:105], v[212:213]
	v_mov_b64_e32 v[106:107], v[214:215]
	v_mov_b64_e32 v[88:89], v[216:217]
	v_mov_b64_e32 v[90:91], v[218:219]
	v_mov_b64_e32 v[72:73], v[220:221]
	v_mov_b64_e32 v[74:75], v[222:223]
	v_mov_b64_e32 v[56:57], v[224:225]
	v_mov_b64_e32 v[58:59], v[226:227]
	v_mov_b64_e32 v[108:109], v[228:229]
	v_mov_b64_e32 v[110:111], v[230:231]
	v_mov_b64_e32 v[92:93], v[232:233]
	v_mov_b64_e32 v[94:95], v[234:235]
	v_mov_b64_e32 v[76:77], v[236:237]
	v_mov_b64_e32 v[78:79], v[238:239]
	v_mov_b64_e32 v[60:61], v[240:241]
	v_mov_b64_e32 v[62:63], v[242:243]
	v_readfirstlane_b32 s32, v112
	s_nop 3
	s_add_i32 s32, s32, 3
	s_cmp_lt_i32 s32, s33
	s_cbranch_scc0 .Ls0_nopf
	s_add_i32 s70, s32, 0
	s_cmp_lt_i32 s70, s17
	s_cselect_b32 s88, s52, s54
	s_cselect_b32 s89, s53, s55
	s_cselect_b32 s71, 0, s17
	s_sub_i32 s70, s70, s71
	s_lshl_b32 s70, s70, 12
	s_add_u32 s88, s88, s70
	s_addc_u32 s89, s89, 0
	global_load_dwordx4 v[168:171], v144, s[88:89]
	global_load_dwordx4 v[172:175], v144, s[88:89] offset:1024
	global_load_dwordx4 v[176:179], v144, s[88:89] offset:2048
	global_load_dwordx4 v[180:183], v144, s[88:89] offset:3072
	s_add_i32 s70, s32, 1
	s_cmp_lt_i32 s70, s17
	s_cselect_b32 s88, s52, s54
	s_cselect_b32 s89, s53, s55
	s_cselect_b32 s71, 0, s17
	s_sub_i32 s70, s70, s71
	s_lshl_b32 s70, s70, 12
	s_add_u32 s88, s88, s70
	s_addc_u32 s89, s89, 0
	global_load_dwordx4 v[196:199], v144, s[88:89]
	global_load_dwordx4 v[200:203], v144, s[88:89] offset:1024
	global_load_dwordx4 v[204:207], v144, s[88:89] offset:2048
	global_load_dwordx4 v[208:211], v144, s[88:89] offset:3072
	s_add_i32 s70, s32, 2
	s_cmp_lt_i32 s70, s17
	s_cselect_b32 s88, s52, s54
	s_cselect_b32 s89, s53, s55
	s_cselect_b32 s71, 0, s17
	s_sub_i32 s70, s70, s71
	s_lshl_b32 s70, s70, 12
	s_add_u32 s88, s88, s70
	s_addc_u32 s89, s89, 0
	global_load_dwordx4 v[212:215], v144, s[88:89]
	global_load_dwordx4 v[216:219], v144, s[88:89] offset:1024
	global_load_dwordx4 v[220:223], v144, s[88:89] offset:2048
	global_load_dwordx4 v[224:227], v144, s[88:89] offset:3072
	s_add_i32 s70, s32, 3
	s_cmp_lt_i32 s70, s17
	s_cselect_b32 s88, s52, s54
	s_cselect_b32 s89, s53, s55
	s_cselect_b32 s71, 0, s17
	s_sub_i32 s70, s70, s71
	s_lshl_b32 s70, s70, 12
	s_add_u32 s88, s88, s70
	s_addc_u32 s89, s89, 0
	global_load_dwordx4 v[228:231], v144, s[88:89]
	global_load_dwordx4 v[232:235], v144, s[88:89] offset:1024
	global_load_dwordx4 v[236:239], v144, s[88:89] offset:2048
	global_load_dwordx4 v[240:243], v144, s[88:89] offset:3072
.Ls0_nopf:
	v_mov_b32_e32 v132, v97
	v_mov_b32_e32 v133, v101
	v_mov_b32_e32 v130, v96
	v_mov_b32_e32 v131, v100
	v_pk_mul_f32 v[132:133], v[132:133], v[132:133]
	v_pk_mul_f32 v[126:127], v[48:49], v[48:49]
	v_pk_fma_f32 v[130:131], v[130:131], v[130:131], v[132:133]
	v_mov_b32_e32 v132, v98
	v_mov_b32_e32 v133, v102
	v_pk_fma_f32 v[130:131], v[132:133], v[132:133], v[130:131]
	v_mov_b32_e32 v132, v99
	v_mov_b32_e32 v133, v103
	v_pk_fma_f32 v[130:131], v[132:133], v[132:133], v[130:131]
	v_mov_b32_e32 v132, v84
	v_mov_b32_e32 v133, v80
	v_pk_fma_f32 v[130:131], v[132:133], v[132:133], v[130:131]
	v_mov_b32_e32 v132, v85
	v_mov_b32_e32 v133, v81
	v_pk_fma_f32 v[130:131], v[132:133], v[132:133], v[130:131]
	v_mov_b32_e32 v132, v86
	v_mov_b32_e32 v133, v82
	v_pk_fma_f32 v[130:131], v[132:133], v[132:133], v[130:131]
	v_mov_b32_e32 v132, v87
	v_mov_b32_e32 v133, v83
	v_pk_fma_f32 v[130:131], v[132:133], v[132:133], v[130:131]
	v_mov_b32_e32 v132, v68
	v_mov_b32_e32 v133, v64
	v_pk_fma_f32 v[130:131], v[132:133], v[132:133], v[130:131]
	v_mov_b32_e32 v132, v69
	v_mov_b32_e32 v133, v65
	v_pk_fma_f32 v[130:131], v[132:133], v[132:133], v[130:131]
	v_mov_b32_e32 v132, v70
	v_mov_b32_e32 v133, v66
	v_pk_mul_f32 v[136:137], v[52:53], v[52:53]
	v_pk_fma_f32 v[130:131], v[132:133], v[132:133], v[130:131]
	v_mov_b32_e32 v132, v71
	v_mov_b32_e32 v133, v67
	v_pk_fma_f32 v[130:131], v[132:133], v[132:133], v[130:131]
	v_mov_b32_e32 v132, v136
	v_mov_b32_e32 v133, v126
	v_pk_mul_f32 v[124:125], v[50:51], v[50:51]
	v_pk_mul_f32 v[134:135], v[54:55], v[54:55]
	v_pk_add_f32 v[130:131], v[132:133], v[130:131]
	v_mov_b32_e32 v126, v137
	v_mov_b32_e32 v136, v109
	v_mov_b32_e32 v137, v105
	v_pk_add_f32 v[126:127], v[126:127], v[130:131]
	v_mov_b32_e32 v130, v134
	v_mov_b32_e32 v131, v124
	v_mov_b32_e32 v124, v135
	v_mov_b32_e32 v134, v108
	v_mov_b32_e32 v135, v104
	v_pk_mul_f32 v[136:137], v[136:137], v[136:137]
	v_pk_add_f32 v[126:127], v[130:131], v[126:127]
	v_pk_fma_f32 v[134:135], v[134:135], v[134:135], v[136:137]
	v_mov_b32_e32 v136, v110
	v_mov_b32_e32 v137, v106
	v_pk_fma_f32 v[134:135], v[136:137], v[136:137], v[134:135]
	v_mov_b32_e32 v136, v111
	v_mov_b32_e32 v137, v107
	v_pk_add_f32 v[124:125], v[124:125], v[126:127]
	v_pk_fma_f32 v[134:135], v[136:137], v[136:137], v[134:135]
	v_mov_b32_e32 v136, v92
	v_mov_b32_e32 v137, v88
	v_mov_b32_e32 v127, v125
	v_mov_b32_e32 v126, v124
	s_nop 1
	v_permlane32_swap_b32 v125, v127
	v_permlane32_swap_b32 v124, v126
	v_pk_fma_f32 v[134:135], v[136:137], v[136:137], v[134:135]
	v_mov_b32_e32 v136, v93
	v_mov_b32_e32 v137, v89
	v_pk_fma_f32 v[134:135], v[136:137], v[136:137], v[134:135]
	v_mov_b32_e32 v136, v94
	v_mov_b32_e32 v137, v90
	v_pk_fma_f32 v[134:135], v[136:137], v[136:137], v[134:135]
	v_mov_b32_e32 v136, v95
	v_mov_b32_e32 v137, v91
	v_pk_fma_f32 v[134:135], v[136:137], v[136:137], v[134:135]
	v_mov_b32_e32 v136, v76
	v_mov_b32_e32 v137, v72
	v_pk_fma_f32 v[134:135], v[136:137], v[136:137], v[134:135]
	v_mov_b32_e32 v136, v77
	v_mov_b32_e32 v137, v73
	s_waitcnt lgkmcnt(0)
	v_pk_add_f32 v[124:125], v[124:125], v[126:127]
	v_pk_fma_f32 v[134:135], v[136:137], v[136:137], v[134:135]
	v_mov_b32_e32 v136, v78
	v_mov_b32_e32 v137, v74
	v_mov_b32_e32 v127, v125
	v_mov_b32_e32 v126, v124
	s_nop 1
	v_permlane16_swap_b32 v125, v127
	v_permlane16_swap_b32 v124, v126
	v_pk_mul_f32 v[132:133], v[56:57], v[56:57]
	v_pk_mul_f32 v[140:141], v[60:61], v[60:61]
	v_pk_fma_f32 v[134:135], v[136:137], v[136:137], v[134:135]
	v_mov_b32_e32 v136, v79
	v_mov_b32_e32 v137, v75
	v_pk_fma_f32 v[134:135], v[136:137], v[136:137], v[134:135]
	v_mov_b32_e32 v136, v140
	v_mov_b32_e32 v137, v132
	v_pk_mul_f32 v[130:131], v[58:59], v[58:59]
	v_pk_mul_f32 v[138:139], v[62:63], v[62:63]
	v_pk_add_f32 v[134:135], v[136:137], v[134:135]
	v_mov_b32_e32 v132, v141
	v_pk_add_f32 v[132:133], v[132:133], v[134:135]
	v_mov_b32_e32 v134, v138
	v_mov_b32_e32 v135, v130
	v_pk_add_f32 v[132:133], v[134:135], v[132:133]
	v_mov_b32_e32 v130, v139
	s_waitcnt lgkmcnt(0)
	v_pk_add_f32 v[124:125], v[124:125], v[126:127]
	v_pk_add_f32 v[130:131], v[130:131], v[132:133]
	s_nop 1
	v_mov_b32_dpp v127, v125 row_ror:8 row_mask:0xf bank_mask:0xf
	v_mov_b32_dpp v126, v124 row_ror:8 row_mask:0xf bank_mask:0xf
	v_mov_b32_e32 v133, v131
	v_mov_b32_e32 v132, v130
	s_nop 1
	v_permlane32_swap_b32 v131, v133
	v_permlane32_swap_b32 v130, v132
	v_pk_add_f32 v[136:137], v[18:19], 1.0 op_sel_hi:[1,0]
	v_lshl_add_u64 v[112:113], v[112:113], 0, 4
	s_waitcnt lgkmcnt(0)
	v_pk_add_f32 v[124:125], v[124:125], v[126:127]
	s_nop 1
	v_mov_b32_dpp v127, v125 row_shl:4 row_mask:0xf bank_mask:0x5
	v_mov_b32_dpp v127, v125 row_shr:4 row_mask:0xf bank_mask:0xa
	s_waitcnt lgkmcnt(0)
	v_pk_add_f32 v[130:131], v[130:131], v[132:133]
	s_nop 1
	v_mov_b32_dpp v126, v124 row_shl:4 row_mask:0xf bank_mask:0x5
	v_mov_b32_dpp v126, v124 row_shr:4 row_mask:0xf bank_mask:0xa
	v_mov_b32_e32 v133, v131
	v_mov_b32_e32 v132, v130
	s_nop 1
	v_permlane16_swap_b32 v131, v133
	v_permlane16_swap_b32 v130, v132
	s_waitcnt lgkmcnt(0)
	v_pk_add_f32 v[124:125], v[124:125], v[126:127]
	s_nop 1
	v_mov_b32_dpp v127, v125 quad_perm:[2,3,0,1] row_mask:0xf bank_mask:0xf
	s_waitcnt lgkmcnt(0)
	v_pk_add_f32 v[130:131], v[130:131], v[132:133]
	s_nop 1
	v_mov_b32_dpp v126, v124 quad_perm:[2,3,0,1] row_mask:0xf bank_mask:0xf
	s_nop 1
	v_mov_b32_dpp v133, v131 row_ror:8 row_mask:0xf bank_mask:0xf
	v_mov_b32_dpp v132, v130 row_ror:8 row_mask:0xf bank_mask:0xf
	s_waitcnt lgkmcnt(0)
	v_pk_add_f32 v[124:125], v[124:125], v[126:127]
	s_nop 1
	v_mov_b32_dpp v127, v125 quad_perm:[1,0,3,2] row_mask:0xf bank_mask:0xf
	s_waitcnt lgkmcnt(0)
	v_pk_add_f32 v[130:131], v[130:131], v[132:133]
	s_nop 1
	v_mov_b32_dpp v126, v124 quad_perm:[1,0,3,2] row_mask:0xf bank_mask:0xf
	s_nop 1
	v_mov_b32_dpp v133, v131 row_shl:4 row_mask:0xf bank_mask:0x5
	v_mov_b32_dpp v132, v130 row_shl:4 row_mask:0xf bank_mask:0x5
	v_mov_b32_dpp v133, v131 row_shr:4 row_mask:0xf bank_mask:0xa
	v_mov_b32_dpp v132, v130 row_shr:4 row_mask:0xf bank_mask:0xa
	s_waitcnt lgkmcnt(0)
	v_pk_add_f32 v[124:125], v[124:125], v[126:127]
	v_mov_b64_e32 v[126:127], s[18:19]
	s_waitcnt lgkmcnt(0)
	v_pk_add_f32 v[130:131], v[130:131], v[132:133]
	v_pk_fma_f32 v[124:125], v[124:125], s[16:17], v[126:127] op_sel_hi:[1,0,0]
	s_nop 1
	v_mov_b32_dpp v133, v131 quad_perm:[2,3,0,1] row_mask:0xf bank_mask:0xf
	v_mov_b32_dpp v132, v130 quad_perm:[2,3,0,1] row_mask:0xf bank_mask:0xf
	v_mul_f32_e32 v134, 0x4b800000, v125
	v_cmp_gt_f32_e32 vcc, s19, v125
	v_cmp_gt_f32_e64 s[0:1], s19, v124
	s_nop 0
	v_cndmask_b32_e32 v125, v125, v134, vcc
	v_rsq_f32_e32 v134, v125
	v_mul_f32_e32 v125, 0x4b800000, v124
	v_cndmask_b32_e64 v124, v124, v125, s[0:1]
	v_rsq_f32_e32 v135, v124
	s_waitcnt lgkmcnt(0)
	v_pk_add_f32 v[124:125], v[130:131], v[132:133]
	s_nop 1
	v_mov_b32_dpp v131, v125 quad_perm:[1,0,3,2] row_mask:0xf bank_mask:0xf
	v_mov_b32_dpp v130, v124 quad_perm:[1,0,3,2] row_mask:0xf bank_mask:0xf
	v_mul_f32_e32 v132, 0x45800000, v134
	v_cndmask_b32_e32 v132, v134, v132, vcc
	v_mul_f32_e32 v133, 0x45800000, v135
	v_pk_mul_f32 v[100:101], v[100:101], v[132:133] op_sel_hi:[1,0]
	s_waitcnt lgkmcnt(0)
	v_pk_add_f32 v[124:125], v[124:125], v[130:131]
	v_pk_mul_f32 v[102:103], v[102:103], v[132:133] op_sel_hi:[1,0]
	v_pk_fma_f32 v[124:125], v[124:125], s[16:17], v[126:127] op_sel_hi:[1,0,0]
	v_pk_mul_f32 v[100:101], v[12:13], v[100:101]
	v_mul_f32_e32 v126, 0x4b800000, v125
	v_cmp_gt_f32_e32 vcc, s19, v125
	v_cmp_gt_f32_e64 s[4:5], s19, v124
	v_pk_mul_f32 v[102:103], v[14:15], v[102:103]
	v_cndmask_b32_e32 v125, v125, v126, vcc
	v_mul_f32_e32 v126, 0x4b800000, v124
	v_rsq_f32_e32 v125, v125
	v_cndmask_b32_e64 v124, v124, v126, s[4:5]
	v_rsq_f32_e32 v127, v124
	v_cndmask_b32_e64 v124, v135, v133, s[0:1]
	v_mul_f32_e32 v126, 0x45800000, v125
	v_cndmask_b32_e32 v126, v125, v126, vcc
	v_mul_f32_e32 v125, 0x45800000, v127
	v_pk_add_f32 v[134:135], v[16:17], 1.0 op_sel_hi:[1,0]
	v_pk_mul_f32 v[96:97], v[96:97], v[124:125] op_sel_hi:[1,0]
	v_pk_mul_f32 v[98:99], v[98:99], v[124:125] op_sel_hi:[1,0]
	v_pk_fma_f32 v[100:101], v[134:135], v[100:101], v[20:21]
	v_pk_fma_f32 v[102:103], v[136:137], v[102:103], v[22:23]
	v_pk_mul_f32 v[96:97], v[12:13], v[96:97]
	v_pk_mul_f32 v[98:99], v[14:15], v[98:99]
	v_cvt_pk_bf16_f32 v100, v100, v101
	v_cvt_pk_bf16_f32 v101, v102, v103
	v_add_co_u32_e32 v102, vcc, s22, v114
	v_pk_fma_f32 v[96:97], v[134:135], v[96:97], v[20:21]
	v_pk_fma_f32 v[98:99], v[136:137], v[98:99], v[22:23]
	v_addc_co_u32_e32 v103, vcc, -1, v115, vcc
	v_cvt_pk_bf16_f32 v96, v96, v97
	v_cvt_pk_bf16_f32 v97, v98, v99
	global_store_dwordx2 v[102:103], v[96:97], off offset:-1536
	v_pk_mul_f32 v[96:97], v[104:105], v[126:127] op_sel_hi:[1,0]
	v_pk_mul_f32 v[98:99], v[106:107], v[126:127] op_sel_hi:[1,0]
	v_pk_mul_f32 v[96:97], v[12:13], v[96:97]
	v_pk_mul_f32 v[98:99], v[14:15], v[98:99]
	v_pk_fma_f32 v[96:97], v[134:135], v[96:97], v[20:21]
	v_pk_fma_f32 v[98:99], v[136:137], v[98:99], v[22:23]
	v_cndmask_b32_e64 v130, v127, v125, s[4:5]
	v_cvt_pk_bf16_f32 v96, v96, v97
	v_cvt_pk_bf16_f32 v97, v98, v99
	global_store_dwordx2 v[114:115], v[96:97], off offset:-3584
	v_pk_mul_f32 v[96:97], v[108:109], v[130:131] op_sel_hi:[1,0]
	v_pk_mul_f32 v[98:99], v[110:111], v[130:131] op_sel_hi:[1,0]
	v_pk_mul_f32 v[96:97], v[12:13], v[96:97]
	v_pk_mul_f32 v[98:99], v[14:15], v[98:99]
	v_pk_fma_f32 v[96:97], v[134:135], v[96:97], v[20:21]
	v_pk_fma_f32 v[98:99], v[136:137], v[98:99], v[22:23]
	v_cvt_pk_bf16_f32 v96, v96, v97
	v_cvt_pk_bf16_f32 v97, v98, v99
	v_pk_mul_f32 v[80:81], v[80:81], v[132:133] op_sel_hi:[1,0]
	v_pk_mul_f32 v[82:83], v[82:83], v[132:133] op_sel_hi:[1,0]
	global_store_dwordx2 v[114:115], v[96:97], off offset:-1536
	v_pk_mul_f32 v[80:81], v[8:9], v[80:81]
	v_pk_add_f32 v[96:97], v[28:29], 1.0 op_sel_hi:[1,0]
	v_pk_mul_f32 v[82:83], v[10:11], v[82:83]
	v_pk_add_f32 v[98:99], v[30:31], 1.0 op_sel_hi:[1,0]
	v_pk_fma_f32 v[80:81], v[96:97], v[80:81], v[24:25]
	v_pk_fma_f32 v[82:83], v[98:99], v[82:83], v[26:27]
	v_cvt_pk_bf16_f32 v80, v80, v81
	v_cvt_pk_bf16_f32 v81, v82, v83
	global_store_dwordx2 v[102:103], v[80:81], off offset:-3072
	v_pk_mul_f32 v[80:81], v[84:85], v[124:125] op_sel_hi:[1,0]
	v_pk_mul_f32 v[82:83], v[86:87], v[124:125] op_sel_hi:[1,0]
	v_pk_mul_f32 v[80:81], v[8:9], v[80:81]
	v_pk_mul_f32 v[82:83], v[10:11], v[82:83]
	v_pk_fma_f32 v[80:81], v[96:97], v[80:81], v[24:25]
	v_pk_fma_f32 v[82:83], v[98:99], v[82:83], v[26:27]
	v_cvt_pk_bf16_f32 v80, v80, v81
	v_cvt_pk_bf16_f32 v81, v82, v83
	global_store_dwordx2 v[102:103], v[80:81], off offset:-1024
	v_pk_mul_f32 v[80:81], v[88:89], v[126:127] op_sel_hi:[1,0]
	v_pk_mul_f32 v[82:83], v[90:91], v[126:127] op_sel_hi:[1,0]
	v_pk_mul_f32 v[80:81], v[8:9], v[80:81]
	v_pk_mul_f32 v[82:83], v[10:11], v[82:83]
	v_pk_fma_f32 v[80:81], v[96:97], v[80:81], v[24:25]
	v_pk_fma_f32 v[82:83], v[98:99], v[82:83], v[26:27]
	v_cvt_pk_bf16_f32 v80, v80, v81
	v_cvt_pk_bf16_f32 v81, v82, v83
	global_store_dwordx2 v[114:115], v[80:81], off offset:-3072
	v_pk_mul_f32 v[80:81], v[92:93], v[130:131] op_sel_hi:[1,0]
	v_pk_mul_f32 v[82:83], v[94:95], v[130:131] op_sel_hi:[1,0]
	v_pk_mul_f32 v[80:81], v[8:9], v[80:81]
	v_pk_mul_f32 v[82:83], v[10:11], v[82:83]
	v_pk_fma_f32 v[80:81], v[96:97], v[80:81], v[24:25]
	v_pk_fma_f32 v[82:83], v[98:99], v[82:83], v[26:27]
	v_cvt_pk_bf16_f32 v80, v80, v81
	v_cvt_pk_bf16_f32 v81, v82, v83
	v_pk_mul_f32 v[64:65], v[64:65], v[132:133] op_sel_hi:[1,0]
	v_pk_mul_f32 v[66:67], v[66:67], v[132:133] op_sel_hi:[1,0]
	global_store_dwordx2 v[114:115], v[80:81], off offset:-1024
	v_pk_mul_f32 v[64:65], v[4:5], v[64:65]
	v_pk_add_f32 v[80:81], v[36:37], 1.0 op_sel_hi:[1,0]
	v_pk_mul_f32 v[66:67], v[6:7], v[66:67]
	v_pk_add_f32 v[82:83], v[38:39], 1.0 op_sel_hi:[1,0]
	v_pk_fma_f32 v[64:65], v[80:81], v[64:65], v[32:33]
	v_pk_fma_f32 v[66:67], v[82:83], v[66:67], v[34:35]
	v_cvt_pk_bf16_f32 v64, v64, v65
	v_cvt_pk_bf16_f32 v65, v66, v67
	global_store_dwordx2 v[102:103], v[64:65], off offset:-2560
	v_pk_mul_f32 v[64:65], v[68:69], v[124:125] op_sel_hi:[1,0]
	v_pk_mul_f32 v[66:67], v[70:71], v[124:125] op_sel_hi:[1,0]
	v_pk_mul_f32 v[64:65], v[4:5], v[64:65]
	v_pk_mul_f32 v[66:67], v[6:7], v[66:67]
	v_pk_fma_f32 v[64:65], v[80:81], v[64:65], v[32:33]
	v_pk_fma_f32 v[66:67], v[82:83], v[66:67], v[34:35]
	v_cvt_pk_bf16_f32 v64, v64, v65
	v_cvt_pk_bf16_f32 v65, v66, v67
	global_store_dwordx2 v[102:103], v[64:65], off offset:-512
	v_pk_mul_f32 v[64:65], v[72:73], v[126:127] op_sel_hi:[1,0]
	v_pk_mul_f32 v[66:67], v[74:75], v[126:127] op_sel_hi:[1,0]
	v_pk_mul_f32 v[64:65], v[4:5], v[64:65]
	v_pk_mul_f32 v[66:67], v[6:7], v[66:67]
	v_pk_fma_f32 v[64:65], v[80:81], v[64:65], v[32:33]
	v_pk_fma_f32 v[66:67], v[82:83], v[66:67], v[34:35]
	v_cvt_pk_bf16_f32 v64, v64, v65
	v_cvt_pk_bf16_f32 v65, v66, v67
	global_store_dwordx2 v[114:115], v[64:65], off offset:-2560
	v_pk_mul_f32 v[64:65], v[76:77], v[130:131] op_sel_hi:[1,0]
	v_pk_mul_f32 v[66:67], v[78:79], v[130:131] op_sel_hi:[1,0]
	v_pk_mul_f32 v[64:65], v[4:5], v[64:65]
	v_pk_mul_f32 v[66:67], v[6:7], v[66:67]
	v_pk_fma_f32 v[64:65], v[80:81], v[64:65], v[32:33]
	v_pk_fma_f32 v[66:67], v[82:83], v[66:67], v[34:35]
	v_cvt_pk_bf16_f32 v64, v64, v65
	v_cvt_pk_bf16_f32 v65, v66, v67
	v_pk_mul_f32 v[48:49], v[48:49], v[132:133] op_sel_hi:[1,0]
	v_pk_mul_f32 v[50:51], v[50:51], v[132:133] op_sel_hi:[1,0]
	global_store_dwordx2 v[114:115], v[64:65], off offset:-512
	v_pk_mul_f32 v[48:49], v[0:1], v[48:49]
	v_pk_add_f32 v[64:65], v[44:45], 1.0 op_sel_hi:[1,0]
	v_pk_mul_f32 v[50:51], v[2:3], v[50:51]
	v_pk_add_f32 v[66:67], v[46:47], 1.0 op_sel_hi:[1,0]
	v_pk_fma_f32 v[48:49], v[64:65], v[48:49], v[40:41]
	v_pk_fma_f32 v[50:51], v[66:67], v[50:51], v[42:43]
	v_cvt_pk_bf16_f32 v48, v48, v49
	v_cvt_pk_bf16_f32 v49, v50, v51
	global_store_dwordx2 v[102:103], v[48:49], off offset:-2048
	v_pk_mul_f32 v[48:49], v[52:53], v[124:125] op_sel_hi:[1,0]
	v_pk_mul_f32 v[50:51], v[54:55], v[124:125] op_sel_hi:[1,0]
	v_pk_mul_f32 v[48:49], v[0:1], v[48:49]
	v_pk_mul_f32 v[50:51], v[2:3], v[50:51]
	v_pk_fma_f32 v[48:49], v[64:65], v[48:49], v[40:41]
	v_pk_fma_f32 v[50:51], v[66:67], v[50:51], v[42:43]
	v_cvt_pk_bf16_f32 v48, v48, v49
	v_cvt_pk_bf16_f32 v49, v50, v51
	global_store_dwordx2 v[114:115], v[48:49], off offset:-4096
	v_pk_mul_f32 v[48:49], v[56:57], v[126:127] op_sel_hi:[1,0]
	v_pk_mul_f32 v[50:51], v[58:59], v[126:127] op_sel_hi:[1,0]
	v_pk_mul_f32 v[48:49], v[0:1], v[48:49]
	v_pk_mul_f32 v[50:51], v[2:3], v[50:51]
	v_pk_fma_f32 v[48:49], v[64:65], v[48:49], v[40:41]
	v_pk_fma_f32 v[50:51], v[66:67], v[50:51], v[42:43]
	v_cvt_pk_bf16_f32 v48, v48, v49
	v_cvt_pk_bf16_f32 v49, v50, v51
	global_store_dwordx2 v[114:115], v[48:49], off offset:-2048
	v_pk_mul_f32 v[48:49], v[60:61], v[130:131] op_sel_hi:[1,0]
	v_pk_mul_f32 v[50:51], v[62:63], v[130:131] op_sel_hi:[1,0]
	v_pk_mul_f32 v[48:49], v[0:1], v[48:49]
	v_pk_mul_f32 v[50:51], v[2:3], v[50:51]
	v_pk_fma_f32 v[48:49], v[64:65], v[48:49], v[40:41]
	v_pk_fma_f32 v[50:51], v[66:67], v[50:51], v[42:43]
	v_cvt_pk_bf16_f32 v48, v48, v49
	v_cvt_pk_bf16_f32 v49, v50, v51
	global_store_dwordx2 v[114:115], v[48:49], off
	v_add_u32_e32 v48, -1, v112
	v_cmp_ge_i32_e32 vcc, v48, v116
	s_or_b64 s[8:9], vcc, s[8:9]
	v_lshl_add_u64 v[114:115], v[114:115], 0, s[20:21]
	global_store_dwordx2 v[102:103], v[100:101], off offset:-3584
	s_andn2_b64 exec, exec, s[8:9]
	s_cbranch_execz .LBB0_76
.LBB0_74:
	v_add_u32_e32 v124, 0xffffdfff, v112
	v_cmp_gt_i32_e32 vcc, 0, v124
	v_lshrrev_b32_e32 v124, 12, v124
	v_add_u32_e32 v124, 1, v124
	v_cndmask_b32_e64 v124, v124, 0, vcc
	v_cmp_ne_u32_e32 vcc, v124, v123
	s_and_saveexec_b64 s[0:1], vcc
	s_cbranch_execz .LBB0_73
	v_mul_u32_u24_e32 v16, 0x2400, v124
	v_mov_b32_e32 v17, v145
	v_lshl_add_u64 v[16:17], v[16:17], 2, s[60:61]
	v_lshl_add_u64 v[36:37], v[16:17], 0, s[14:15]
	v_lshlrev_b32_e32 v18, 2, v160
	v_mov_b32_e32 v19, v145
	v_lshl_add_u64 v[38:39], v[16:17], 0, v[144:145]
	v_lshl_add_u64 v[16:17], v[36:37], 0, v[144:145]
	v_lshl_add_u64 v[28:29], v[36:37], 0, v[18:19]
	v_lshlrev_b32_e32 v32, 2, v161
	v_mov_b32_e32 v33, v145
	global_load_dwordx4 v[20:23], v[38:39], off
	global_load_dwordx4 v[24:27], v[38:39], off offset:1024
	s_nop 0
	global_load_dwordx4 v[16:19], v[16:17], off
	s_nop 0
	global_load_dwordx4 v[28:31], v[28:29], off
	v_lshl_add_u64 v[44:45], v[36:37], 0, v[32:33]
	global_load_dwordx4 v[32:35], v[38:39], off offset:2048
	global_load_dwordx4 v[40:43], v[38:39], off offset:3072
	v_lshlrev_b32_e32 v38, 2, v162
	v_mov_b32_e32 v39, v145
	v_lshl_add_u64 v[46:47], v[36:37], 0, v[38:39]
	global_load_dwordx4 v[36:39], v[44:45], off
	s_nop 0
	global_load_dwordx4 v[44:47], v[46:47], off
	v_mov_b32_e32 v123, v124
	s_waitcnt vmcnt(0)
	s_branch .LBB0_73
